# GEMM K-loops: last 2 LDS-DMA pieces of the heavy load segments moved past the barrier into the MFMA segment (vmcnt 8->6 there)
# speedup vs baseline: 1.0028x; 1.0028x over previous
.LBB0_1010:
	s_add_i32 s42, s38, 2
	s_add_u32 s43, s36, 0x80
	s_addc_u32 s39, s37, 0
	s_add_i32 s69, 0, 0x10000
	s_cmp_eq_u32 s55, s38
	s_cselect_b32 s39, s31, s39
	s_cselect_b32 s38, s30, s43
	s_cselect_b32 s67, s35, s17
	s_cselect_b32 s66, s34, s16
	s_add_i32 s43, 0, 0x14000
	v_add_u32_e32 v152, s69, v145
	v_add_u32_e32 v168, s43, v145
	ds_read_b128 v[130:133], v152
	ds_read_b128 v[140:143], v152 offset:1024
	ds_read_b128 v[148:151], v152 offset:2048
	ds_read_b128 v[152:155], v152 offset:3072
	ds_read_b128 v[156:159], v168
	ds_read_b128 v[160:163], v168 offset:1024
	ds_read_b128 v[164:167], v168 offset:2048
	ds_read_b128 v[168:171], v168 offset:3072
	v_lshl_add_u64 v[192:193], s[36:37], 0, v[138:139]
	s_add_i32 m0, s13, 0xc000
	ds_read_b128 v[172:175], v147
	ds_read_b128 v[176:179], v147 offset:1024
	ds_read_b128 v[180:183], v147 offset:2048
	ds_read_b128 v[184:187], v147 offset:3072
	ds_read_b128 v[188:191], v147 offset:4096
	ds_read_b128 v[196:199], v147 offset:5120
	ds_read_b128 v[200:203], v147 offset:6144
	ds_read_b128 v[204:207], v147 offset:7168
	global_load_lds_dwordx4 v[192:193], off
	v_lshl_add_u64 v[192:193], s[36:37], 0, v[136:137]
	s_add_i32 m0, s13, 0xe000
	s_nop 0
	global_load_lds_dwordx4 v[192:193], off
	s_waitcnt vmcnt(8)
	s_waitcnt lgkmcnt(0)
	s_barrier
	s_setprio 1
	s_waitcnt lgkmcnt(0)
	v_mfma_f32_16x16x32_bf16 v[126:129], v[130:133], v[172:175], v[126:129]
	v_mfma_f32_16x16x32_bf16 v[94:97], v[148:151], v[172:175], v[94:97]
	v_mfma_f32_16x16x32_bf16 v[122:125], v[130:133], v[180:183], v[122:125]
	v_mfma_f32_16x16x32_bf16 v[90:93], v[148:151], v[180:183], v[90:93]
	v_mfma_f32_16x16x32_bf16 v[118:121], v[130:133], v[188:191], v[118:121]
	v_mfma_f32_16x16x32_bf16 v[86:89], v[148:151], v[188:191], v[86:89]
	v_mfma_f32_16x16x32_bf16 v[114:117], v[130:133], v[200:203], v[114:117]
	v_mfma_f32_16x16x32_bf16 v[82:85], v[148:151], v[200:203], v[82:85]
	v_mfma_f32_16x16x32_bf16 v[126:129], v[140:143], v[176:179], v[126:129]
	v_mfma_f32_16x16x32_bf16 v[94:97], v[152:155], v[176:179], v[94:97]
	v_mfma_f32_16x16x32_bf16 v[122:125], v[140:143], v[184:187], v[122:125]
	v_mfma_f32_16x16x32_bf16 v[90:93], v[152:155], v[184:187], v[90:93]
	v_mfma_f32_16x16x32_bf16 v[118:121], v[140:143], v[196:199], v[118:121]
	v_mfma_f32_16x16x32_bf16 v[86:89], v[152:155], v[196:199], v[86:89]
	v_mfma_f32_16x16x32_bf16 v[114:117], v[140:143], v[204:207], v[114:117]
	v_mfma_f32_16x16x32_bf16 v[82:85], v[152:155], v[204:207], v[82:85]
	s_setprio 0
	s_setprio 1
	v_mfma_f32_16x16x32_bf16 v[62:65], v[156:159], v[172:175], v[62:65]
	v_mfma_f32_16x16x32_bf16 v[30:33], v[164:167], v[172:175], v[30:33]
	v_mfma_f32_16x16x32_bf16 v[58:61], v[156:159], v[180:183], v[58:61]
	v_mfma_f32_16x16x32_bf16 v[26:29], v[164:167], v[180:183], v[26:29]
	v_mfma_f32_16x16x32_bf16 v[54:57], v[156:159], v[188:191], v[54:57]
	v_mfma_f32_16x16x32_bf16 v[22:25], v[164:167], v[188:191], v[22:25]
	v_mfma_f32_16x16x32_bf16 v[50:53], v[156:159], v[200:203], v[50:53]
	v_mfma_f32_16x16x32_bf16 v[18:21], v[164:167], v[200:203], v[18:21]
	v_mfma_f32_16x16x32_bf16 v[62:65], v[160:163], v[176:179], v[62:65]
	v_mfma_f32_16x16x32_bf16 v[30:33], v[168:171], v[176:179], v[30:33]
	v_mfma_f32_16x16x32_bf16 v[58:61], v[160:163], v[184:187], v[58:61]
	v_mfma_f32_16x16x32_bf16 v[26:29], v[168:171], v[184:187], v[26:29]
	v_mfma_f32_16x16x32_bf16 v[54:57], v[160:163], v[196:199], v[54:57]
	v_mfma_f32_16x16x32_bf16 v[22:25], v[168:171], v[196:199], v[22:25]
	v_mfma_f32_16x16x32_bf16 v[50:53], v[160:163], v[204:207], v[50:53]
	v_mfma_f32_16x16x32_bf16 v[18:21], v[168:171], v[204:207], v[18:21]
	s_setprio 0
	s_barrier
	s_add_i32 s69, s69, s3
	v_lshl_add_u64 v[192:193], s[66:67], 0, v[0:1]
	s_mov_b32 m0, s69
	ds_read_b128 v[172:175], v147 offset:16384
	ds_read_b128 v[176:179], v147 offset:17408
	ds_read_b128 v[180:183], v147 offset:18432
	ds_read_b128 v[184:187], v147 offset:19456
	ds_read_b128 v[188:191], v147 offset:20480
	ds_read_b128 v[196:199], v147 offset:21504
	ds_read_b128 v[200:203], v147 offset:22528
	ds_read_b128 v[204:207], v147 offset:23552
	global_load_lds_dwordx4 v[192:193], off
	s_add_i32 m0, s69, 0x2000
	v_lshl_add_u64 v[208:209], s[66:67], 0, v[134:135]
	s_add_u32 s66, s66, s18
	s_addc_u32 s67, s67, 0
	s_add_i32 s43, s43, s3
	global_load_lds_dwordx4 v[208:209], off
	v_lshl_add_u64 v[218:219], s[66:67], 0, v[0:1]
	s_mov_b32 m0, s43
	v_lshl_add_u64 v[220:221], s[66:67], 0, v[134:135]
	global_load_lds_dwordx4 v[218:219], off
	s_add_i32 m0, s43, 0x2000
	v_lshl_add_u64 v[222:223], s[38:39], 0, v[0:1]
	global_load_lds_dwordx4 v[220:221], off
	v_lshl_add_u64 v[224:225], s[38:39], 0, v[134:135]
	s_waitcnt vmcnt(6)
	s_waitcnt lgkmcnt(0)
	s_barrier
	s_setprio 1
	s_waitcnt lgkmcnt(0)
	v_mfma_f32_16x16x32_bf16 v[110:113], v[130:133], v[172:175], v[110:113]
	v_mfma_f32_16x16x32_bf16 v[78:81], v[148:151], v[172:175], v[78:81]
	s_mov_b32 m0, s13
	v_mfma_f32_16x16x32_bf16 v[106:109], v[130:133], v[180:183], v[106:109]
	global_load_lds_dwordx4 v[222:223], off
	v_mfma_f32_16x16x32_bf16 v[74:77], v[148:151], v[180:183], v[74:77]
	v_mfma_f32_16x16x32_bf16 v[102:105], v[130:133], v[188:191], v[102:105]
	s_mov_b32 m0, s23
	v_mfma_f32_16x16x32_bf16 v[70:73], v[148:151], v[188:191], v[70:73]
	global_load_lds_dwordx4 v[224:225], off
	v_mfma_f32_16x16x32_bf16 v[98:101], v[130:133], v[200:203], v[98:101]
	v_mfma_f32_16x16x32_bf16 v[66:69], v[148:151], v[200:203], v[66:69]
	v_mfma_f32_16x16x32_bf16 v[110:113], v[140:143], v[176:179], v[110:113]
	v_mfma_f32_16x16x32_bf16 v[78:81], v[152:155], v[176:179], v[78:81]
	v_mfma_f32_16x16x32_bf16 v[106:109], v[140:143], v[184:187], v[106:109]
	v_mfma_f32_16x16x32_bf16 v[74:77], v[152:155], v[184:187], v[74:77]
	v_mfma_f32_16x16x32_bf16 v[102:105], v[140:143], v[196:199], v[102:105]
	v_mfma_f32_16x16x32_bf16 v[70:73], v[152:155], v[196:199], v[70:73]
	v_mfma_f32_16x16x32_bf16 v[98:101], v[140:143], v[204:207], v[98:101]
	v_mfma_f32_16x16x32_bf16 v[66:69], v[152:155], v[204:207], v[66:69]
	s_setprio 0
	s_setprio 1
	v_mfma_f32_16x16x32_bf16 v[46:49], v[156:159], v[172:175], v[46:49]
	v_mfma_f32_16x16x32_bf16 v[14:17], v[164:167], v[172:175], v[14:17]
	v_mfma_f32_16x16x32_bf16 v[42:45], v[156:159], v[180:183], v[42:45]
	v_mfma_f32_16x16x32_bf16 v[10:13], v[164:167], v[180:183], v[10:13]
	v_mfma_f32_16x16x32_bf16 v[38:41], v[156:159], v[188:191], v[38:41]
	v_mfma_f32_16x16x32_bf16 v[6:9], v[164:167], v[188:191], v[6:9]
	v_mfma_f32_16x16x32_bf16 v[34:37], v[156:159], v[200:203], v[34:37]
	v_mfma_f32_16x16x32_bf16 v[2:5], v[164:167], v[200:203], v[2:5]
	v_mfma_f32_16x16x32_bf16 v[46:49], v[160:163], v[176:179], v[46:49]
	v_mfma_f32_16x16x32_bf16 v[14:17], v[168:171], v[176:179], v[14:17]
	v_mfma_f32_16x16x32_bf16 v[42:45], v[160:163], v[184:187], v[42:45]
	v_mfma_f32_16x16x32_bf16 v[10:13], v[168:171], v[184:187], v[10:13]
	v_mfma_f32_16x16x32_bf16 v[38:41], v[160:163], v[196:199], v[38:41]
	v_mfma_f32_16x16x32_bf16 v[6:9], v[168:171], v[196:199], v[6:9]
	v_mfma_f32_16x16x32_bf16 v[34:37], v[160:163], v[204:207], v[34:37]
	v_mfma_f32_16x16x32_bf16 v[2:5], v[168:171], v[204:207], v[2:5]
	s_setprio 0
	s_barrier
	s_add_i32 s43, 0, 0x18000
	s_add_i32 s66, 0, 0x1c000
	v_add_u32_e32 v152, s43, v145
	v_add_u32_e32 v168, s66, v145
	ds_read_b128 v[130:133], v152
	ds_read_b128 v[140:143], v152 offset:1024
	ds_read_b128 v[148:151], v152 offset:2048
	ds_read_b128 v[152:155], v152 offset:3072
	ds_read_b128 v[156:159], v168
	ds_read_b128 v[160:163], v168 offset:1024
	ds_read_b128 v[164:167], v168 offset:2048
	ds_read_b128 v[168:171], v168 offset:3072
	s_add_u32 s38, s38, s18
	s_addc_u32 s39, s39, 0
	s_mov_b32 m0, s44
	v_lshl_add_u64 v[226:227], s[38:39], 0, v[0:1]
	ds_read_b128 v[172:175], v147 offset:32768
	ds_read_b128 v[176:179], v147 offset:33792
	ds_read_b128 v[180:183], v147 offset:34816
	ds_read_b128 v[184:187], v147 offset:35840
	ds_read_b128 v[188:191], v147 offset:36864
	ds_read_b128 v[196:199], v147 offset:37888
	ds_read_b128 v[200:203], v147 offset:38912
	ds_read_b128 v[204:207], v147 offset:39936
	global_load_lds_dwordx4 v[226:227], off
	v_lshl_add_u64 v[226:227], s[38:39], 0, v[134:135]
	s_mov_b32 m0, s45
	s_nop 0
	global_load_lds_dwordx4 v[226:227], off
	s_waitcnt vmcnt(8)
	s_waitcnt lgkmcnt(0)
	s_barrier
	s_setprio 1
	s_waitcnt lgkmcnt(0)
	v_mfma_f32_16x16x32_bf16 v[126:129], v[130:133], v[172:175], v[126:129]
	v_mfma_f32_16x16x32_bf16 v[94:97], v[148:151], v[172:175], v[94:97]
	v_mfma_f32_16x16x32_bf16 v[122:125], v[130:133], v[180:183], v[122:125]
	v_mfma_f32_16x16x32_bf16 v[90:93], v[148:151], v[180:183], v[90:93]
	v_mfma_f32_16x16x32_bf16 v[118:121], v[130:133], v[188:191], v[118:121]
	v_mfma_f32_16x16x32_bf16 v[86:89], v[148:151], v[188:191], v[86:89]
	v_mfma_f32_16x16x32_bf16 v[114:117], v[130:133], v[200:203], v[114:117]
	v_mfma_f32_16x16x32_bf16 v[82:85], v[148:151], v[200:203], v[82:85]
	v_mfma_f32_16x16x32_bf16 v[126:129], v[140:143], v[176:179], v[126:129]
	v_mfma_f32_16x16x32_bf16 v[94:97], v[152:155], v[176:179], v[94:97]
	v_mfma_f32_16x16x32_bf16 v[122:125], v[140:143], v[184:187], v[122:125]
	v_mfma_f32_16x16x32_bf16 v[90:93], v[152:155], v[184:187], v[90:93]
	v_mfma_f32_16x16x32_bf16 v[118:121], v[140:143], v[196:199], v[118:121]
	v_mfma_f32_16x16x32_bf16 v[86:89], v[152:155], v[196:199], v[86:89]
	v_mfma_f32_16x16x32_bf16 v[114:117], v[140:143], v[204:207], v[114:117]
	v_mfma_f32_16x16x32_bf16 v[82:85], v[152:155], v[204:207], v[82:85]
	s_setprio 0
	s_setprio 1
	v_mfma_f32_16x16x32_bf16 v[62:65], v[156:159], v[172:175], v[62:65]
	v_mfma_f32_16x16x32_bf16 v[30:33], v[164:167], v[172:175], v[30:33]
	v_mfma_f32_16x16x32_bf16 v[58:61], v[156:159], v[180:183], v[58:61]
	v_mfma_f32_16x16x32_bf16 v[26:29], v[164:167], v[180:183], v[26:29]
	v_mfma_f32_16x16x32_bf16 v[54:57], v[156:159], v[188:191], v[54:57]
	v_mfma_f32_16x16x32_bf16 v[22:25], v[164:167], v[188:191], v[22:25]
	v_mfma_f32_16x16x32_bf16 v[50:53], v[156:159], v[200:203], v[50:53]
	v_mfma_f32_16x16x32_bf16 v[18:21], v[164:167], v[200:203], v[18:21]
	v_mfma_f32_16x16x32_bf16 v[62:65], v[160:163], v[176:179], v[62:65]
	v_mfma_f32_16x16x32_bf16 v[30:33], v[168:171], v[176:179], v[30:33]
	v_mfma_f32_16x16x32_bf16 v[58:61], v[160:163], v[184:187], v[58:61]
	v_mfma_f32_16x16x32_bf16 v[26:29], v[168:171], v[184:187], v[26:29]
	v_mfma_f32_16x16x32_bf16 v[54:57], v[160:163], v[196:199], v[54:57]
	v_mfma_f32_16x16x32_bf16 v[22:25], v[168:171], v[196:199], v[22:25]
	v_mfma_f32_16x16x32_bf16 v[50:53], v[160:163], v[204:207], v[50:53]
	v_mfma_f32_16x16x32_bf16 v[18:21], v[168:171], v[204:207], v[18:21]
	s_setprio 0
	s_barrier
	s_add_i32 s38, s43, s3
	v_lshl_add_u64 v[192:193], v[192:193], 0, s[88:89]
	s_mov_b32 m0, s38
	ds_read_b128 v[172:175], v147 offset:49152
	ds_read_b128 v[176:179], v147 offset:50176
	ds_read_b128 v[180:183], v147 offset:51200
	ds_read_b128 v[184:187], v147 offset:52224
	ds_read_b128 v[188:191], v147 offset:53248
	ds_read_b128 v[196:199], v147 offset:54272
	ds_read_b128 v[200:203], v147 offset:55296
	ds_read_b128 v[204:207], v147 offset:56320
	global_load_lds_dwordx4 v[192:193], off
	v_lshl_add_u64 v[192:193], v[208:209], 0, s[88:89]
	s_add_i32 m0, s38, 0x2000
	s_add_i32 s38, s66, s3
	global_load_lds_dwordx4 v[192:193], off
	v_lshl_add_u64 v[192:193], v[218:219], 0, s[88:89]
	s_mov_b32 m0, s38
	s_nop 0
	global_load_lds_dwordx4 v[192:193], off
	v_lshl_add_u64 v[192:193], v[220:221], 0, s[88:89]
	s_add_i32 m0, s38, 0x2000
	s_nop 0
	global_load_lds_dwordx4 v[192:193], off
	s_waitcnt vmcnt(6)
	s_waitcnt lgkmcnt(0)
	s_barrier
	s_setprio 1
	s_waitcnt lgkmcnt(0)
	v_mfma_f32_16x16x32_bf16 v[110:113], v[130:133], v[172:175], v[110:113]
	v_mfma_f32_16x16x32_bf16 v[78:81], v[148:151], v[172:175], v[78:81]
	v_lshl_add_u64 v[192:193], v[222:223], 0, s[88:89]
	s_mov_b32 m0, s52
	v_mfma_f32_16x16x32_bf16 v[106:109], v[130:133], v[180:183], v[106:109]
	global_load_lds_dwordx4 v[192:193], off
	v_mfma_f32_16x16x32_bf16 v[74:77], v[148:151], v[180:183], v[74:77]
	v_mfma_f32_16x16x32_bf16 v[102:105], v[130:133], v[188:191], v[102:105]
	v_lshl_add_u64 v[192:193], v[224:225], 0, s[88:89]
	s_mov_b32 m0, s53
	v_mfma_f32_16x16x32_bf16 v[70:73], v[148:151], v[188:191], v[70:73]
	global_load_lds_dwordx4 v[192:193], off
	v_mfma_f32_16x16x32_bf16 v[98:101], v[130:133], v[200:203], v[98:101]
	v_mfma_f32_16x16x32_bf16 v[66:69], v[148:151], v[200:203], v[66:69]
	v_mfma_f32_16x16x32_bf16 v[110:113], v[140:143], v[176:179], v[110:113]
	v_mfma_f32_16x16x32_bf16 v[78:81], v[152:155], v[176:179], v[78:81]
	v_mfma_f32_16x16x32_bf16 v[106:109], v[140:143], v[184:187], v[106:109]
	v_mfma_f32_16x16x32_bf16 v[74:77], v[152:155], v[184:187], v[74:77]
	v_mfma_f32_16x16x32_bf16 v[102:105], v[140:143], v[196:199], v[102:105]
	v_mfma_f32_16x16x32_bf16 v[70:73], v[152:155], v[196:199], v[70:73]
	v_mfma_f32_16x16x32_bf16 v[98:101], v[140:143], v[204:207], v[98:101]
	v_mfma_f32_16x16x32_bf16 v[66:69], v[152:155], v[204:207], v[66:69]
	s_setprio 0
	s_setprio 1
	v_mfma_f32_16x16x32_bf16 v[46:49], v[156:159], v[172:175], v[46:49]
	v_mfma_f32_16x16x32_bf16 v[14:17], v[164:167], v[172:175], v[14:17]
	v_mfma_f32_16x16x32_bf16 v[42:45], v[156:159], v[180:183], v[42:45]
	v_mfma_f32_16x16x32_bf16 v[10:13], v[164:167], v[180:183], v[10:13]
	v_mfma_f32_16x16x32_bf16 v[38:41], v[156:159], v[188:191], v[38:41]
	v_mfma_f32_16x16x32_bf16 v[6:9], v[164:167], v[188:191], v[6:9]
	v_mfma_f32_16x16x32_bf16 v[34:37], v[156:159], v[200:203], v[34:37]
	v_mfma_f32_16x16x32_bf16 v[2:5], v[164:167], v[200:203], v[2:5]
	v_mfma_f32_16x16x32_bf16 v[46:49], v[160:163], v[176:179], v[46:49]
	v_mfma_f32_16x16x32_bf16 v[14:17], v[168:171], v[176:179], v[14:17]
	v_mfma_f32_16x16x32_bf16 v[42:45], v[160:163], v[184:187], v[42:45]
	v_mfma_f32_16x16x32_bf16 v[10:13], v[168:171], v[184:187], v[10:13]
	v_mfma_f32_16x16x32_bf16 v[38:41], v[160:163], v[196:199], v[38:41]
	v_mfma_f32_16x16x32_bf16 v[6:9], v[168:171], v[196:199], v[6:9]
	v_mfma_f32_16x16x32_bf16 v[34:37], v[160:163], v[204:207], v[34:37]
	v_mfma_f32_16x16x32_bf16 v[2:5], v[168:171], v[204:207], v[2:5]
	s_setprio 0
	s_barrier
	s_add_u32 s16, s16, 0x100
	s_addc_u32 s17, s17, 0
	s_add_u32 s36, s36, 0x100
	s_addc_u32 s37, s37, 0
	s_cmp_ge_u32 s42, s51
	s_mov_b32 s38, s42
	s_cbranch_scc0 .LBB0_1010
	s_nop 0
	s_nop 0
	s_nop 0

.LBB0_1187:
	s_add_i32 s35, s17, 2
	s_add_u32 s44, s18, 0x80
	s_addc_u32 s45, s19, 0
	s_add_i32 s63, 0, 0x10000
	s_cmp_eq_u32 s9, s17
	s_cselect_b32 s45, s7, s45
	s_cselect_b32 s44, s6, s44
	v_add_u32_e32 v0, s63, v175
	s_cselect_b32 s67, s15, s16
	s_cselect_b32 s66, s14, s5
	s_add_i32 s17, 0, 0x14000
	ds_read_b128 v[144:147], v0
	ds_read_b128 v[148:151], v0 offset:1024
	ds_read_b128 v[152:155], v0 offset:2048
	ds_read_b128 v[156:159], v0 offset:3072
	v_add_u32_e32 v0, s17, v175
	ds_read_b128 v[160:163], v0
	ds_read_b128 v[178:181], v0 offset:1024
	ds_read_b128 v[182:185], v0 offset:2048
	ds_read_b128 v[186:189], v0 offset:3072
	v_lshl_add_u64 v[208:209], s[18:19], 0, v[142:143]
	s_add_i32 m0, s29, 0xc000
	ds_read_b128 v[190:193], v176
	ds_read_b128 v[196:199], v176 offset:1024
	ds_read_b128 v[200:203], v176 offset:2048
	ds_read_b128 v[204:207], v176 offset:3072
	ds_read_b128 v[218:221], v176 offset:4096
	ds_read_b128 v[222:225], v176 offset:5120
	ds_read_b128 v[226:229], v176 offset:6144
	ds_read_b128 v[230:233], v176 offset:7168
	global_load_lds_dwordx4 v[208:209], off
	v_lshl_add_u64 v[208:209], s[18:19], 0, v[140:141]
	s_add_i32 m0, s29, 0xe000
	s_nop 0
	global_load_lds_dwordx4 v[208:209], off
	s_waitcnt vmcnt(8)
	s_waitcnt lgkmcnt(0)
	s_barrier
	s_setprio 1
	s_waitcnt lgkmcnt(0)
	v_mfma_f32_16x16x32_bf16 v[126:129], v[144:147], v[190:193], v[126:129]
	v_mfma_f32_16x16x32_bf16 v[122:125], v[152:155], v[190:193], v[122:125]
	v_mfma_f32_16x16x32_bf16 v[110:113], v[144:147], v[200:203], v[110:113]
	v_mfma_f32_16x16x32_bf16 v[106:109], v[152:155], v[200:203], v[106:109]
	v_mfma_f32_16x16x32_bf16 v[94:97], v[144:147], v[218:221], v[94:97]
	v_mfma_f32_16x16x32_bf16 v[90:93], v[152:155], v[218:221], v[90:93]
	v_mfma_f32_16x16x32_bf16 v[78:81], v[144:147], v[226:229], v[78:81]
	v_mfma_f32_16x16x32_bf16 v[74:77], v[152:155], v[226:229], v[74:77]
	v_mfma_f32_16x16x32_bf16 v[126:129], v[148:151], v[196:199], v[126:129]
	v_mfma_f32_16x16x32_bf16 v[122:125], v[156:159], v[196:199], v[122:125]
	v_mfma_f32_16x16x32_bf16 v[110:113], v[148:151], v[204:207], v[110:113]
	v_mfma_f32_16x16x32_bf16 v[106:109], v[156:159], v[204:207], v[106:109]
	v_mfma_f32_16x16x32_bf16 v[94:97], v[148:151], v[222:225], v[94:97]
	v_mfma_f32_16x16x32_bf16 v[90:93], v[156:159], v[222:225], v[90:93]
	v_mfma_f32_16x16x32_bf16 v[78:81], v[148:151], v[230:233], v[78:81]
	v_mfma_f32_16x16x32_bf16 v[74:77], v[156:159], v[230:233], v[74:77]
	s_setprio 0
	s_setprio 1
	v_mfma_f32_16x16x32_bf16 v[118:121], v[160:163], v[190:193], v[118:121]
	v_mfma_f32_16x16x32_bf16 v[114:117], v[182:185], v[190:193], v[114:117]
	v_mfma_f32_16x16x32_bf16 v[102:105], v[160:163], v[200:203], v[102:105]
	v_mfma_f32_16x16x32_bf16 v[98:101], v[182:185], v[200:203], v[98:101]
	v_mfma_f32_16x16x32_bf16 v[86:89], v[160:163], v[218:221], v[86:89]
	v_mfma_f32_16x16x32_bf16 v[82:85], v[182:185], v[218:221], v[82:85]
	v_mfma_f32_16x16x32_bf16 v[70:73], v[160:163], v[226:229], v[70:73]
	v_mfma_f32_16x16x32_bf16 v[66:69], v[182:185], v[226:229], v[66:69]
	v_mfma_f32_16x16x32_bf16 v[118:121], v[178:181], v[196:199], v[118:121]
	v_mfma_f32_16x16x32_bf16 v[114:117], v[186:189], v[196:199], v[114:117]
	v_mfma_f32_16x16x32_bf16 v[102:105], v[178:181], v[204:207], v[102:105]
	v_mfma_f32_16x16x32_bf16 v[98:101], v[186:189], v[204:207], v[98:101]
	v_mfma_f32_16x16x32_bf16 v[86:89], v[178:181], v[222:225], v[86:89]
	v_mfma_f32_16x16x32_bf16 v[82:85], v[186:189], v[222:225], v[82:85]
	v_mfma_f32_16x16x32_bf16 v[70:73], v[178:181], v[230:233], v[70:73]
	v_mfma_f32_16x16x32_bf16 v[66:69], v[186:189], v[230:233], v[66:69]
	s_setprio 0
	s_barrier
	s_add_i32 s63, s63, s28
	v_lshl_add_u64 v[208:209], s[66:67], 0, v[132:133]
	s_mov_b32 m0, s63
	ds_read_b128 v[190:193], v176 offset:16384
	ds_read_b128 v[196:199], v176 offset:17408
	ds_read_b128 v[200:203], v176 offset:18432
	ds_read_b128 v[204:207], v176 offset:19456
	ds_read_b128 v[218:221], v176 offset:20480
	ds_read_b128 v[222:225], v176 offset:21504
	ds_read_b128 v[226:229], v176 offset:22528
	ds_read_b128 v[230:233], v176 offset:23552
	global_load_lds_dwordx4 v[208:209], off
	s_add_i32 m0, s63, 0x2000
	v_lshl_add_u64 v[234:235], s[66:67], 0, v[136:137]
	s_add_u32 s66, s66, s55
	s_addc_u32 s67, s67, 0
	s_add_i32 s17, s17, s28
	global_load_lds_dwordx4 v[234:235], off
	v_lshl_add_u64 v[242:243], s[66:67], 0, v[132:133]
	s_mov_b32 m0, s17
	v_lshl_add_u64 v[244:245], s[66:67], 0, v[136:137]
	global_load_lds_dwordx4 v[242:243], off
	s_add_i32 m0, s17, 0x2000
	v_lshl_add_u64 v[246:247], s[44:45], 0, v[130:131]
	global_load_lds_dwordx4 v[244:245], off
	v_lshl_add_u64 v[248:249], s[44:45], 0, v[134:135]
	s_waitcnt vmcnt(6)
	s_waitcnt lgkmcnt(0)
	s_barrier
	s_setprio 1
	s_waitcnt lgkmcnt(0)
	v_mfma_f32_16x16x32_bf16 v[62:65], v[144:147], v[190:193], v[62:65]
	v_mfma_f32_16x16x32_bf16 v[58:61], v[152:155], v[190:193], v[58:61]
	s_mov_b32 m0, s29
	v_mfma_f32_16x16x32_bf16 v[46:49], v[144:147], v[200:203], v[46:49]
	global_load_lds_dwordx4 v[246:247], off
	v_mfma_f32_16x16x32_bf16 v[42:45], v[152:155], v[200:203], v[42:45]
	v_mfma_f32_16x16x32_bf16 v[30:33], v[144:147], v[218:221], v[30:33]
	s_mov_b32 m0, s26
	v_mfma_f32_16x16x32_bf16 v[26:29], v[152:155], v[218:221], v[26:29]
	global_load_lds_dwordx4 v[248:249], off
	v_mfma_f32_16x16x32_bf16 v[14:17], v[144:147], v[226:229], v[14:17]
	v_mfma_f32_16x16x32_bf16 v[10:13], v[152:155], v[226:229], v[10:13]
	v_mfma_f32_16x16x32_bf16 v[62:65], v[148:151], v[196:199], v[62:65]
	v_mfma_f32_16x16x32_bf16 v[58:61], v[156:159], v[196:199], v[58:61]
	v_mfma_f32_16x16x32_bf16 v[46:49], v[148:151], v[204:207], v[46:49]
	v_mfma_f32_16x16x32_bf16 v[42:45], v[156:159], v[204:207], v[42:45]
	v_mfma_f32_16x16x32_bf16 v[30:33], v[148:151], v[222:225], v[30:33]
	v_mfma_f32_16x16x32_bf16 v[26:29], v[156:159], v[222:225], v[26:29]
	v_mfma_f32_16x16x32_bf16 v[14:17], v[148:151], v[230:233], v[14:17]
	v_mfma_f32_16x16x32_bf16 v[10:13], v[156:159], v[230:233], v[10:13]
	s_setprio 0
	s_setprio 1
	v_mfma_f32_16x16x32_bf16 v[54:57], v[160:163], v[190:193], v[54:57]
	v_mfma_f32_16x16x32_bf16 v[50:53], v[182:185], v[190:193], v[50:53]
	v_mfma_f32_16x16x32_bf16 v[38:41], v[160:163], v[200:203], v[38:41]
	v_mfma_f32_16x16x32_bf16 v[34:37], v[182:185], v[200:203], v[34:37]
	v_mfma_f32_16x16x32_bf16 v[22:25], v[160:163], v[218:221], v[22:25]
	v_mfma_f32_16x16x32_bf16 v[18:21], v[182:185], v[218:221], v[18:21]
	v_mfma_f32_16x16x32_bf16 v[6:9], v[160:163], v[226:229], v[6:9]
	v_mfma_f32_16x16x32_bf16 v[2:5], v[182:185], v[226:229], v[2:5]
	v_mfma_f32_16x16x32_bf16 v[54:57], v[178:181], v[196:199], v[54:57]
	v_mfma_f32_16x16x32_bf16 v[50:53], v[186:189], v[196:199], v[50:53]
	v_mfma_f32_16x16x32_bf16 v[38:41], v[178:181], v[204:207], v[38:41]
	v_mfma_f32_16x16x32_bf16 v[34:37], v[186:189], v[204:207], v[34:37]
	v_mfma_f32_16x16x32_bf16 v[22:25], v[178:181], v[222:225], v[22:25]
	v_mfma_f32_16x16x32_bf16 v[18:21], v[186:189], v[222:225], v[18:21]
	v_mfma_f32_16x16x32_bf16 v[6:9], v[178:181], v[230:233], v[6:9]
	v_mfma_f32_16x16x32_bf16 v[2:5], v[186:189], v[230:233], v[2:5]
	s_setprio 0
	s_barrier
	s_add_i32 s17, 0, 0x18000
	v_add_u32_e32 v0, s17, v175
	s_add_i32 s63, 0, 0x1c000
	ds_read_b128 v[144:147], v0
	ds_read_b128 v[148:151], v0 offset:1024
	ds_read_b128 v[152:155], v0 offset:2048
	ds_read_b128 v[156:159], v0 offset:3072
	v_add_u32_e32 v0, s63, v175
	ds_read_b128 v[160:163], v0
	ds_read_b128 v[178:181], v0 offset:1024
	ds_read_b128 v[182:185], v0 offset:2048
	ds_read_b128 v[186:189], v0 offset:3072
	s_add_u32 s44, s44, s34
	s_addc_u32 s45, s45, 0
	s_mov_b32 m0, s27
	v_lshl_add_u64 v[250:251], s[44:45], 0, v[130:131]
	ds_read_b128 v[190:193], v176 offset:32768
	ds_read_b128 v[196:199], v176 offset:33792
	ds_read_b128 v[200:203], v176 offset:34816
	ds_read_b128 v[204:207], v176 offset:35840
	ds_read_b128 v[218:221], v176 offset:36864
	ds_read_b128 v[222:225], v176 offset:37888
	ds_read_b128 v[226:229], v176 offset:38912
	ds_read_b128 v[230:233], v176 offset:39936
	global_load_lds_dwordx4 v[250:251], off
	v_lshl_add_u64 v[250:251], s[44:45], 0, v[134:135]
	s_mov_b32 m0, s8
	s_nop 0
	global_load_lds_dwordx4 v[250:251], off
	s_waitcnt vmcnt(8)
	s_waitcnt lgkmcnt(0)
	s_barrier
	s_setprio 1
	s_waitcnt lgkmcnt(0)
	v_mfma_f32_16x16x32_bf16 v[126:129], v[144:147], v[190:193], v[126:129]
	v_mfma_f32_16x16x32_bf16 v[122:125], v[152:155], v[190:193], v[122:125]
	v_mfma_f32_16x16x32_bf16 v[110:113], v[144:147], v[200:203], v[110:113]
	v_mfma_f32_16x16x32_bf16 v[106:109], v[152:155], v[200:203], v[106:109]
	v_mfma_f32_16x16x32_bf16 v[94:97], v[144:147], v[218:221], v[94:97]
	v_mfma_f32_16x16x32_bf16 v[90:93], v[152:155], v[218:221], v[90:93]
	v_mfma_f32_16x16x32_bf16 v[78:81], v[144:147], v[226:229], v[78:81]
	v_mfma_f32_16x16x32_bf16 v[74:77], v[152:155], v[226:229], v[74:77]
	v_mfma_f32_16x16x32_bf16 v[126:129], v[148:151], v[196:199], v[126:129]
	v_mfma_f32_16x16x32_bf16 v[122:125], v[156:159], v[196:199], v[122:125]
	v_mfma_f32_16x16x32_bf16 v[110:113], v[148:151], v[204:207], v[110:113]
	v_mfma_f32_16x16x32_bf16 v[106:109], v[156:159], v[204:207], v[106:109]
	v_mfma_f32_16x16x32_bf16 v[94:97], v[148:151], v[222:225], v[94:97]
	v_mfma_f32_16x16x32_bf16 v[90:93], v[156:159], v[222:225], v[90:93]
	v_mfma_f32_16x16x32_bf16 v[78:81], v[148:151], v[230:233], v[78:81]
	v_mfma_f32_16x16x32_bf16 v[74:77], v[156:159], v[230:233], v[74:77]
	s_setprio 0
	s_setprio 1
	v_mfma_f32_16x16x32_bf16 v[118:121], v[160:163], v[190:193], v[118:121]
	v_mfma_f32_16x16x32_bf16 v[114:117], v[182:185], v[190:193], v[114:117]
	v_mfma_f32_16x16x32_bf16 v[102:105], v[160:163], v[200:203], v[102:105]
	v_mfma_f32_16x16x32_bf16 v[98:101], v[182:185], v[200:203], v[98:101]
	v_mfma_f32_16x16x32_bf16 v[86:89], v[160:163], v[218:221], v[86:89]
	v_mfma_f32_16x16x32_bf16 v[82:85], v[182:185], v[218:221], v[82:85]
	v_mfma_f32_16x16x32_bf16 v[70:73], v[160:163], v[226:229], v[70:73]
	v_mfma_f32_16x16x32_bf16 v[66:69], v[182:185], v[226:229], v[66:69]
	v_mfma_f32_16x16x32_bf16 v[118:121], v[178:181], v[196:199], v[118:121]
	v_mfma_f32_16x16x32_bf16 v[114:117], v[186:189], v[196:199], v[114:117]
	v_mfma_f32_16x16x32_bf16 v[102:105], v[178:181], v[204:207], v[102:105]
	v_mfma_f32_16x16x32_bf16 v[98:101], v[186:189], v[204:207], v[98:101]
	v_mfma_f32_16x16x32_bf16 v[86:89], v[178:181], v[222:225], v[86:89]
	v_mfma_f32_16x16x32_bf16 v[82:85], v[186:189], v[222:225], v[82:85]
	v_mfma_f32_16x16x32_bf16 v[70:73], v[178:181], v[230:233], v[70:73]
	v_mfma_f32_16x16x32_bf16 v[66:69], v[186:189], v[230:233], v[66:69]
	s_setprio 0
	s_barrier
	s_add_i32 s17, s17, s28
	v_lshl_add_u64 v[208:209], v[208:209], 0, s[88:89]
	s_mov_b32 m0, s17
	ds_read_b128 v[190:193], v176 offset:49152
	ds_read_b128 v[196:199], v176 offset:50176
	ds_read_b128 v[200:203], v176 offset:51200
	ds_read_b128 v[204:207], v176 offset:52224
	ds_read_b128 v[218:221], v176 offset:53248
	ds_read_b128 v[222:225], v176 offset:54272
	ds_read_b128 v[226:229], v176 offset:55296
	ds_read_b128 v[230:233], v176 offset:56320
	global_load_lds_dwordx4 v[208:209], off
	v_lshl_add_u64 v[208:209], v[234:235], 0, s[88:89]
	s_add_i32 m0, s17, 0x2000
	s_add_i32 s17, s63, s28
	global_load_lds_dwordx4 v[208:209], off
	v_lshl_add_u64 v[208:209], v[242:243], 0, s[88:89]
	s_mov_b32 m0, s17
	s_nop 0
	global_load_lds_dwordx4 v[208:209], off
	v_lshl_add_u64 v[208:209], v[244:245], 0, s[88:89]
	s_add_i32 m0, s17, 0x2000
	s_nop 0
	global_load_lds_dwordx4 v[208:209], off
	s_waitcnt vmcnt(6)
	s_waitcnt lgkmcnt(0)
	s_barrier
	s_setprio 1
	s_waitcnt lgkmcnt(0)
	v_mfma_f32_16x16x32_bf16 v[62:65], v[144:147], v[190:193], v[62:65]
	v_mfma_f32_16x16x32_bf16 v[58:61], v[152:155], v[190:193], v[58:61]
	v_lshl_add_u64 v[208:209], v[246:247], 0, s[88:89]
	s_mov_b32 m0, s10
	v_mfma_f32_16x16x32_bf16 v[46:49], v[144:147], v[200:203], v[46:49]
	global_load_lds_dwordx4 v[208:209], off
	v_mfma_f32_16x16x32_bf16 v[42:45], v[152:155], v[200:203], v[42:45]
	v_mfma_f32_16x16x32_bf16 v[30:33], v[144:147], v[218:221], v[30:33]
	v_lshl_add_u64 v[208:209], v[248:249], 0, s[88:89]
	s_mov_b32 m0, s11
	v_mfma_f32_16x16x32_bf16 v[26:29], v[152:155], v[218:221], v[26:29]
	global_load_lds_dwordx4 v[208:209], off
	v_mfma_f32_16x16x32_bf16 v[14:17], v[144:147], v[226:229], v[14:17]
	v_mfma_f32_16x16x32_bf16 v[10:13], v[152:155], v[226:229], v[10:13]
	v_mfma_f32_16x16x32_bf16 v[62:65], v[148:151], v[196:199], v[62:65]
	v_mfma_f32_16x16x32_bf16 v[58:61], v[156:159], v[196:199], v[58:61]
	v_mfma_f32_16x16x32_bf16 v[46:49], v[148:151], v[204:207], v[46:49]
	v_mfma_f32_16x16x32_bf16 v[42:45], v[156:159], v[204:207], v[42:45]
	v_mfma_f32_16x16x32_bf16 v[30:33], v[148:151], v[222:225], v[30:33]
	v_mfma_f32_16x16x32_bf16 v[26:29], v[156:159], v[222:225], v[26:29]
	v_mfma_f32_16x16x32_bf16 v[14:17], v[148:151], v[230:233], v[14:17]
	v_mfma_f32_16x16x32_bf16 v[10:13], v[156:159], v[230:233], v[10:13]
	s_setprio 0
	s_setprio 1
	v_mfma_f32_16x16x32_bf16 v[54:57], v[160:163], v[190:193], v[54:57]
	v_mfma_f32_16x16x32_bf16 v[50:53], v[182:185], v[190:193], v[50:53]
	v_mfma_f32_16x16x32_bf16 v[38:41], v[160:163], v[200:203], v[38:41]
	v_mfma_f32_16x16x32_bf16 v[34:37], v[182:185], v[200:203], v[34:37]
	v_mfma_f32_16x16x32_bf16 v[22:25], v[160:163], v[218:221], v[22:25]
	v_mfma_f32_16x16x32_bf16 v[18:21], v[182:185], v[218:221], v[18:21]
	v_mfma_f32_16x16x32_bf16 v[6:9], v[160:163], v[226:229], v[6:9]
	v_mfma_f32_16x16x32_bf16 v[2:5], v[182:185], v[226:229], v[2:5]
	v_mfma_f32_16x16x32_bf16 v[54:57], v[178:181], v[196:199], v[54:57]
	v_mfma_f32_16x16x32_bf16 v[50:53], v[186:189], v[196:199], v[50:53]
	v_mfma_f32_16x16x32_bf16 v[38:41], v[178:181], v[204:207], v[38:41]
	v_mfma_f32_16x16x32_bf16 v[34:37], v[186:189], v[204:207], v[34:37]
	v_mfma_f32_16x16x32_bf16 v[22:25], v[178:181], v[222:225], v[22:25]
	v_mfma_f32_16x16x32_bf16 v[18:21], v[186:189], v[222:225], v[18:21]
	v_mfma_f32_16x16x32_bf16 v[6:9], v[178:181], v[230:233], v[6:9]
	v_mfma_f32_16x16x32_bf16 v[2:5], v[186:189], v[230:233], v[2:5]
	s_setprio 0
	s_barrier
	s_add_u32 s5, s5, 0x100
	s_addc_u32 s16, s16, 0
	s_add_u32 s18, s18, 0x100
	s_addc_u32 s19, s19, 0
	s_cmp_ge_u32 s35, s12
	s_mov_b32 s17, s35
	s_cbranch_scc0 .LBB0_1187
	s_nop 0
	s_nop 0
	s_nop 0
